# P0 fourier fold on f32 matrix cores (v_mfma_f32_16x16x4_f32, f32 operands/accumulate) instead of VALU fma chains; P0 round rotation 13->9; on top of v125
# speedup vs baseline: 1.0031x; 1.0031x over previous
.LBB0_20:
	s_mov_b32 s100, s92
	s_bfe_u32 s101, s92, 0x10003
	s_cmp_eq_u32 s101, 0
	s_cbranch_scc1 .Lp0r_done
	s_and_b32 s101, s92, 0xff
	s_lshr_b32 s100, s92, 8
	s_add_i32 s100, s100, 9
	s_cmpk_lt_u32 s101, 0x4d
	s_cselect_b32 s0, 18, 17
	s_cmp_lt_u32 s100, s0
	s_cbranch_scc1 .Lp0r_nowrap
	s_sub_u32 s100, s100, s0

.LBB0_71:
	v_readlane_b32 s82, v254, 3
	v_readlane_b32 s83, v254, 4
	s_andn2_saveexec_b64 s[82:83], s[82:83]
	s_cbranch_execz .LBB0_77
	v_and_b32_e32 v1, 0xff, v200
	v_lshrrev_b32_e32 v2, 8, v200
	v_lshlrev_b32_e32 v154, 16, v2
	v_add_u32_e32 v154, 0x400, v154
	s_movk_i32 s86, 0x80
	v_cmp_gt_u32_e32 vcc, s86, v1
	s_barrier
	s_and_saveexec_b64 s[86:87], vcc
	s_cbranch_execz .Lff_t
	v_cvt_f32_ubyte0_e32 v3, v1
	v_mul_f32_e32 v3, 0x3c000000, v3
	v_sin_f32_e32 v5, v3
	v_cos_f32_e32 v3, v3
	v_lshl_add_u32 v6, v1, 2, v154
	ds_write2st64_b32 v6, v3, v5 offset1:2
.Lff_t:
	s_or_b64 exec, exec, s[86:87]
	s_lshr_b32 s93, s101, 1
	s_bfe_u32 s100, s93, 0x30007
	s_lshl_b32 s100, s100, 18
	s_and_b32 s86, s93, 15
	s_lshl_b32 s86, s86, 7
	s_add_u32 s100, s100, s86
	s_bfe_u32 s86, s93, 0x30004
	s_lshl_b32 s86, s86, 4
	v_and_b32_e32 v155, 63, v200
	v_and_b32_e32 v156, 15, v155
	v_lshrrev_b32_e32 v157, 4, v155
	v_bfe_u32 v158, v200, 6, 2
	v_and_b32_e32 v159, 1, v158
	v_lshlrev_b32_e32 v160, 11, v157
	v_lshl_add_u32 v160, v2, 6, v160
	v_lshl_add_u32 v160, v156, 2, v160
	v_add_u32_e32 v160, s100, v160
	v_add_u32_e32 v161, s86, v156
	v_mul_u32_u24_e32 v162, v161, v157
	v_lshlrev_b32_e32 v162, 2, v162
	v_lshlrev_b32_e32 v161, 4, v161
	v_lshl_add_u32 v163, v159, 9, v154
	v_mov_b32_e32 v196, 0
	v_mov_b32_e32 v197, 0
	v_mov_b32_e32 v198, 0
	v_mov_b32_e32 v199, 0
	v_mov_b32_e32 v42, 0
	v_mov_b32_e32 v43, 0
	v_mov_b32_e32 v44, 0
	v_mov_b32_e32 v45, 0
	s_waitcnt lgkmcnt(0)
	s_barrier
	v_readfirstlane_b32 s87, v158
	s_cmp_lt_u32 s87, 2
	s_cbranch_scc0 .Lff_done
	s_movk_i32 s87, 0x1fc
	global_load_dword v164, v160, s[56:57]
	v_add_u32_e32 v160, 0x2000, v160
	global_load_dword v165, v160, s[56:57]
	v_add_u32_e32 v160, 0x2000, v160
	global_load_dword v166, v160, s[56:57]
	v_add_u32_e32 v160, 0x2000, v160
	global_load_dword v167, v160, s[56:57]
	v_add_u32_e32 v160, 0x2000, v160
	global_load_dword v168, v160, s[56:57]
	v_add_u32_e32 v160, 0x2000, v160
	global_load_dword v169, v160, s[56:57]
	v_add_u32_e32 v160, 0x2000, v160
	global_load_dword v170, v160, s[56:57]
	v_add_u32_e32 v160, 0x2000, v160
	global_load_dword v171, v160, s[56:57]
	v_add_u32_e32 v160, 0x2000, v160
	global_load_dword v172, v160, s[56:57]
	v_add_u32_e32 v160, 0x2000, v160
	global_load_dword v173, v160, s[56:57]
	v_add_u32_e32 v160, 0x2000, v160
	global_load_dword v174, v160, s[56:57]
	v_add_u32_e32 v160, 0x2000, v160
	global_load_dword v175, v160, s[56:57]
	v_add_u32_e32 v160, 0x2000, v160
	global_load_dword v176, v160, s[56:57]
	v_add_u32_e32 v160, 0x2000, v160
	global_load_dword v177, v160, s[56:57]
	v_add_u32_e32 v160, 0x2000, v160
	global_load_dword v178, v160, s[56:57]
	v_add_u32_e32 v160, 0x2000, v160
	global_load_dword v179, v160, s[56:57]
	v_add_u32_e32 v160, 0x2000, v160
	global_load_dword v180, v160, s[56:57]
	v_add_u32_e32 v160, 0x2000, v160
	global_load_dword v181, v160, s[56:57]
	v_add_u32_e32 v160, 0x2000, v160
	global_load_dword v182, v160, s[56:57]
	v_add_u32_e32 v160, 0x2000, v160
	global_load_dword v183, v160, s[56:57]
	v_add_u32_e32 v160, 0x2000, v160
	global_load_dword v184, v160, s[56:57]
	v_add_u32_e32 v160, 0x2000, v160
	global_load_dword v185, v160, s[56:57]
	v_add_u32_e32 v160, 0x2000, v160
	global_load_dword v186, v160, s[56:57]
	v_add_u32_e32 v160, 0x2000, v160
	global_load_dword v187, v160, s[56:57]
	v_add_u32_e32 v160, 0x2000, v160
	global_load_dword v188, v160, s[56:57]
	v_add_u32_e32 v160, 0x2000, v160
	global_load_dword v189, v160, s[56:57]
	v_add_u32_e32 v160, 0x2000, v160
	global_load_dword v190, v160, s[56:57]
	v_add_u32_e32 v160, 0x2000, v160
	global_load_dword v191, v160, s[56:57]
	v_add_u32_e32 v160, 0x2000, v160
	global_load_dword v192, v160, s[56:57]
	v_add_u32_e32 v160, 0x2000, v160
	global_load_dword v193, v160, s[56:57]
	v_add_u32_e32 v160, 0x2000, v160
	global_load_dword v194, v160, s[56:57]
	v_add_u32_e32 v160, 0x2000, v160
	global_load_dword v195, v160, s[56:57]
	v_and_or_b32 v0, v162, s87, v163
	ds_read_b32 v10, v0
	v_add_u32_e32 v162, v162, v161
	v_and_or_b32 v0, v162, s87, v163
	ds_read_b32 v11, v0
	v_add_u32_e32 v162, v162, v161
	v_and_or_b32 v0, v162, s87, v163
	ds_read_b32 v12, v0
	v_add_u32_e32 v162, v162, v161
	v_and_or_b32 v0, v162, s87, v163
	ds_read_b32 v13, v0
	v_add_u32_e32 v162, v162, v161
	v_and_or_b32 v0, v162, s87, v163
	ds_read_b32 v14, v0
	v_add_u32_e32 v162, v162, v161
	v_and_or_b32 v0, v162, s87, v163
	ds_read_b32 v15, v0
	v_add_u32_e32 v162, v162, v161
	v_and_or_b32 v0, v162, s87, v163
	ds_read_b32 v16, v0
	v_add_u32_e32 v162, v162, v161
	v_and_or_b32 v0, v162, s87, v163
	ds_read_b32 v17, v0
	v_add_u32_e32 v162, v162, v161
	v_and_or_b32 v0, v162, s87, v163
	ds_read_b32 v18, v0
	v_add_u32_e32 v162, v162, v161
	v_and_or_b32 v0, v162, s87, v163
	ds_read_b32 v19, v0
	v_add_u32_e32 v162, v162, v161
	v_and_or_b32 v0, v162, s87, v163
	ds_read_b32 v20, v0
	v_add_u32_e32 v162, v162, v161
	v_and_or_b32 v0, v162, s87, v163
	ds_read_b32 v21, v0
	v_add_u32_e32 v162, v162, v161
	v_and_or_b32 v0, v162, s87, v163
	ds_read_b32 v22, v0
	v_add_u32_e32 v162, v162, v161
	v_and_or_b32 v0, v162, s87, v163
	ds_read_b32 v23, v0
	v_add_u32_e32 v162, v162, v161
	v_and_or_b32 v0, v162, s87, v163
	ds_read_b32 v24, v0
	v_add_u32_e32 v162, v162, v161
	v_and_or_b32 v0, v162, s87, v163
	ds_read_b32 v25, v0
	v_add_u32_e32 v162, v162, v161
	v_and_or_b32 v0, v162, s87, v163
	ds_read_b32 v26, v0
	v_add_u32_e32 v162, v162, v161
	v_and_or_b32 v0, v162, s87, v163
	ds_read_b32 v27, v0
	v_add_u32_e32 v162, v162, v161
	v_and_or_b32 v0, v162, s87, v163
	ds_read_b32 v28, v0
	v_add_u32_e32 v162, v162, v161
	v_and_or_b32 v0, v162, s87, v163
	ds_read_b32 v29, v0
	v_add_u32_e32 v162, v162, v161
	v_and_or_b32 v0, v162, s87, v163
	ds_read_b32 v30, v0
	v_add_u32_e32 v162, v162, v161
	v_and_or_b32 v0, v162, s87, v163
	ds_read_b32 v31, v0
	v_add_u32_e32 v162, v162, v161
	v_and_or_b32 v0, v162, s87, v163
	ds_read_b32 v32, v0
	v_add_u32_e32 v162, v162, v161
	v_and_or_b32 v0, v162, s87, v163
	ds_read_b32 v33, v0
	v_add_u32_e32 v162, v162, v161
	v_and_or_b32 v0, v162, s87, v163
	ds_read_b32 v34, v0
	v_add_u32_e32 v162, v162, v161
	v_and_or_b32 v0, v162, s87, v163
	ds_read_b32 v35, v0
	v_add_u32_e32 v162, v162, v161
	v_and_or_b32 v0, v162, s87, v163
	ds_read_b32 v36, v0
	v_add_u32_e32 v162, v162, v161
	v_and_or_b32 v0, v162, s87, v163
	ds_read_b32 v37, v0
	v_add_u32_e32 v162, v162, v161
	v_and_or_b32 v0, v162, s87, v163
	ds_read_b32 v38, v0
	v_add_u32_e32 v162, v162, v161
	v_and_or_b32 v0, v162, s87, v163
	ds_read_b32 v39, v0
	v_add_u32_e32 v162, v162, v161
	v_and_or_b32 v0, v162, s87, v163
	ds_read_b32 v40, v0
	v_add_u32_e32 v162, v162, v161
	v_and_or_b32 v0, v162, s87, v163
	ds_read_b32 v41, v0
	s_lshr_b32 s100, s93, 9
	s_lshl_b32 s100, s100, 20
	s_bfe_u32 s87, s93, 0x20007
	s_lshl_b32 s87, s87, 8
	s_add_u32 s100, s100, s87
	s_lshl_b32 s86, s86, 1
	s_add_u32 s100, s100, s86
	s_and_b32 s86, s93, 15
	s_lshl_b32 s86, s86, 15
	s_add_u32 s100, s100, s86
	v_lshlrev_b32_e32 v0, 4, v2
	v_add_u32_e32 v0, v0, v156
	v_lshlrev_b32_e32 v0, 10, v0
	v_lshl_add_u32 v0, v159, 19, v0
	v_lshl_add_u32 v0, v157, 3, v0
	v_add_u32_e32 v0, s100, v0
	s_waitcnt lgkmcnt(0)
	s_waitcnt vmcnt(31)
	v_mfma_f32_16x16x4_f32 v[196:199], v10, v164, v[196:199]
	s_waitcnt vmcnt(30)
	v_mfma_f32_16x16x4_f32 v[42:45], v11, v165, v[42:45]
	s_waitcnt vmcnt(29)
	v_mfma_f32_16x16x4_f32 v[196:199], v12, v166, v[196:199]
	s_waitcnt vmcnt(28)
	v_mfma_f32_16x16x4_f32 v[42:45], v13, v167, v[42:45]
	s_waitcnt vmcnt(27)
	v_mfma_f32_16x16x4_f32 v[196:199], v14, v168, v[196:199]
	s_waitcnt vmcnt(26)
	v_mfma_f32_16x16x4_f32 v[42:45], v15, v169, v[42:45]
	s_waitcnt vmcnt(25)
	v_mfma_f32_16x16x4_f32 v[196:199], v16, v170, v[196:199]
	s_waitcnt vmcnt(24)
	v_mfma_f32_16x16x4_f32 v[42:45], v17, v171, v[42:45]
	s_waitcnt vmcnt(23)
	v_mfma_f32_16x16x4_f32 v[196:199], v18, v172, v[196:199]
	s_waitcnt vmcnt(22)
	v_mfma_f32_16x16x4_f32 v[42:45], v19, v173, v[42:45]
	s_waitcnt vmcnt(21)
	v_mfma_f32_16x16x4_f32 v[196:199], v20, v174, v[196:199]
	s_waitcnt vmcnt(20)
	v_mfma_f32_16x16x4_f32 v[42:45], v21, v175, v[42:45]
	s_waitcnt vmcnt(19)
	v_mfma_f32_16x16x4_f32 v[196:199], v22, v176, v[196:199]
	s_waitcnt vmcnt(18)
	v_mfma_f32_16x16x4_f32 v[42:45], v23, v177, v[42:45]
	s_waitcnt vmcnt(17)
	v_mfma_f32_16x16x4_f32 v[196:199], v24, v178, v[196:199]
	s_waitcnt vmcnt(16)
	v_mfma_f32_16x16x4_f32 v[42:45], v25, v179, v[42:45]
	s_waitcnt vmcnt(15)
	v_mfma_f32_16x16x4_f32 v[196:199], v26, v180, v[196:199]
	s_waitcnt vmcnt(14)
	v_mfma_f32_16x16x4_f32 v[42:45], v27, v181, v[42:45]
	s_waitcnt vmcnt(13)
	v_mfma_f32_16x16x4_f32 v[196:199], v28, v182, v[196:199]
	s_waitcnt vmcnt(12)
	v_mfma_f32_16x16x4_f32 v[42:45], v29, v183, v[42:45]
	s_waitcnt vmcnt(11)
	v_mfma_f32_16x16x4_f32 v[196:199], v30, v184, v[196:199]
	s_waitcnt vmcnt(10)
	v_mfma_f32_16x16x4_f32 v[42:45], v31, v185, v[42:45]
	s_waitcnt vmcnt(9)
	v_mfma_f32_16x16x4_f32 v[196:199], v32, v186, v[196:199]
	s_waitcnt vmcnt(8)
	v_mfma_f32_16x16x4_f32 v[42:45], v33, v187, v[42:45]
	s_waitcnt vmcnt(7)
	v_mfma_f32_16x16x4_f32 v[196:199], v34, v188, v[196:199]
	s_waitcnt vmcnt(6)
	v_mfma_f32_16x16x4_f32 v[42:45], v35, v189, v[42:45]
	s_waitcnt vmcnt(5)
	v_mfma_f32_16x16x4_f32 v[196:199], v36, v190, v[196:199]
	s_waitcnt vmcnt(4)
	v_mfma_f32_16x16x4_f32 v[42:45], v37, v191, v[42:45]
	s_waitcnt vmcnt(3)
	v_mfma_f32_16x16x4_f32 v[196:199], v38, v192, v[196:199]
	s_waitcnt vmcnt(2)
	v_mfma_f32_16x16x4_f32 v[42:45], v39, v193, v[42:45]
	s_waitcnt vmcnt(1)
	v_mfma_f32_16x16x4_f32 v[196:199], v40, v194, v[196:199]
	s_waitcnt vmcnt(0)
	v_mfma_f32_16x16x4_f32 v[42:45], v41, v195, v[42:45]
	s_nop 15
	s_nop 3
	v_pk_add_f32 v[196:197], v[196:197], v[42:43]
	v_pk_add_f32 v[198:199], v[198:199], v[44:45]
	v_mov_b32_e32 v8, 0x3db504f3
	s_nop 0
	v_pk_mul_f32 v[196:197], v[196:197], v[8:9] op_sel_hi:[1,0]
	v_pk_mul_f32 v[198:199], v[198:199], v[8:9] op_sel_hi:[1,0]
	s_nop 0
	v_cvt_pk_bf16_f32 v6, v196, v197
	v_cvt_pk_bf16_f32 v7, v198, v199
	s_nop 0
	global_store_dwordx2 v0, v[6:7], s[4:5]
.Lff_done:
.LBB0_77:
	s_or_b64 exec, exec, s[82:83]
	v_readlane_b32 s82, v254, 1
	v_readlane_b32 s83, v254, 2
